# LayerNorm phase: next step's x/y rows are brought into LDS by LDS-DMA while the current rows are normalised (per-wave 12 KB buffer); gMLP LayerNorm pass rows requested one step ahead
# speedup vs baseline: 1.0082x; 1.0002x over previous
.LBB0_635:
	s_and_b64 vcc, exec, s[30:31]
	s_cbranch_vccz .LBB0_616
	s_mov_b64 s[4:5], s[0:1]
	s_load_dwordx2 s[62:63], s[4:5], 0xd8
	s_mov_b64 s[92:93], s[0:1]
	s_mov_b64 s[34:35], s[0:1]
	s_mov_b64 s[4:5], s[0:1]
	s_load_dwordx2 s[30:31], s[4:5], 0xd8
	s_mov_b64 s[4:5], s[0:1]
	s_load_dwordx2 s[40:41], s[4:5], 0x98
	s_ashr_i32 s4, s96, 7
	s_ashr_i32 s5, s4, 31
	s_lshl_b64 s[70:71], s[4:5], 14
	s_and_saveexec_b64 s[76:77], s[26:27]
	s_cbranch_execz .LBB0_639
	s_load_dwordx2 s[4:5], s[92:93], 0x80
	s_nop 0
	s_load_dwordx2 s[34:35], s[34:35], 0x88
	v_readlane_b32 s50, v242, 26
	v_readlane_b32 s51, v242, 27
	s_lshl_b64 s[50:51], s[50:51], 2
	s_waitcnt lgkmcnt(0)
	s_add_u32 s4, s4, s50
	s_addc_u32 s5, s5, s51
	v_lshlrev_b32_e32 v6, 2, v62
	s_add_u32 s34, s34, s50
	s_addc_u32 s35, s35, s51
	global_load_dwordx4 v[2:5], v6, s[4:5]
	s_nop 0
	global_load_dwordx4 v[6:9], v6, s[34:35]
	s_and_b32 s2, s46, 0x3f80
	v_lshl_add_u64 v[12:13], s[62:63], 0, v[78:79]
	s_mov_b64 s[4:5], 0x9800c00
	v_lshl_add_u64 v[12:13], v[12:13], 0, s[4:5]
	s_add_u32 s4, s2, s70
	s_addc_u32 s5, 0, s71
	v_lshl_add_u64 v[14:15], s[4:5], 0, v[60:61]
	v_mad_u64_u32 v[12:13], s[4:5], v14, s64, v[12:13]
	v_mad_i32_i24 v13, v15, s64, v13
	s_mov_b64 s[92:93], 0
	v_mov_b32_e32 v14, v160
	v_mov_b32_e32 v15, v159
	v_mov_b32_e32 v252, 0xc000
	v_mov_b32_e32 v253, 0
	v_lshl_add_u64 v[252:253], v[12:13], 0, v[252:253]
	global_load_dwordx2 v[244:245], v[12:13], off
	global_load_dwordx2 v[246:247], v[252:253], off
.LBB0_638:
	s_waitcnt vmcnt(0)
	v_mov_b64_e32 v[16:17], v[244:245]
	v_mov_b64_e32 v[250:251], v[246:247]
	v_lshl_add_u64 v[12:13], v[12:13], 0, s[94:95]
	v_mov_b32_e32 v252, 0xc000
	v_mov_b32_e32 v253, 0
	v_lshl_add_u64 v[252:253], v[12:13], 0, v[252:253]
	global_load_dwordx2 v[244:245], v[12:13], off
	global_load_dwordx2 v[246:247], v[252:253], off
	s_mov_b32 s2, 0x3b800000
	v_add_u32_e32 v15, 16, v15
	v_and_b32_e32 v19, 0xffff0000, v16
	v_lshlrev_b32_e32 v18, 16, v16
	v_and_b32_e32 v21, 0xffff0000, v17
	v_lshlrev_b32_e32 v20, 16, v17
	v_mov_b64_e32 v[16:17], v[250:251]
	s_nop 0
	v_and_b32_e32 v23, 0xffff0000, v16
	v_lshlrev_b32_e32 v22, 16, v16
	v_and_b32_e32 v25, 0xffff0000, v17
	v_lshlrev_b32_e32 v24, 16, v17
	v_add_f32_e32 v16, v21, v20
	v_add_f32_e32 v17, v19, v18
	v_add_f32_e32 v16, v17, v16
	v_add_f32_e32 v26, v23, v22
	s_nop 0
	v_add_f32_dpp v16, v16, v16 quad_perm:[1,0,3,2] row_mask:0xf bank_mask:0xf bound_ctrl:1
	s_nop 1
	v_add_f32_dpp v16, v16, v16 quad_perm:[2,3,0,1] row_mask:0xf bank_mask:0xf bound_ctrl:1
	s_nop 1
	v_add_f32_dpp v16, v16, v16 row_half_mirror row_mask:0xf bank_mask:0xf bound_ctrl:1
	s_nop 1
	v_add_f32_dpp v16, v16, v16 row_mirror row_mask:0xf bank_mask:0xf bound_ctrl:1
	v_mov_b32_e32 v17, v16
	s_nop 1
	v_permlane16_swap_b32 v16, v17
	s_nop 1
	s_nop 0
	v_add_f32_e32 v16, v16, v17
	v_mov_b32_e32 v17, v16
	s_nop 1
	v_permlane32_swap_b32 v16, v17
	s_nop 1
	s_nop 0
	v_add_f32_e32 v16, v16, v17
	v_add_f32_e32 v17, v25, v24
	v_add_f32_e32 v17, v26, v17
	v_fmac_f32_e32 v21, 0xbb800000, v16
	v_fmac_f32_e32 v19, 0xbb800000, v16
	v_add_f32_dpp v17, v17, v17 quad_perm:[1,0,3,2] row_mask:0xf bank_mask:0xf bound_ctrl:1
	v_fmac_f32_e32 v20, 0xbb800000, v16
	v_fmac_f32_e32 v18, 0xbb800000, v16
	v_add_f32_dpp v17, v17, v17 quad_perm:[2,3,0,1] row_mask:0xf bank_mask:0xf bound_ctrl:1
	v_mul_f32_e32 v16, v19, v19
	v_fmac_f32_e32 v16, v18, v18
	v_add_f32_dpp v17, v17, v17 row_half_mirror row_mask:0xf bank_mask:0xf bound_ctrl:1
	s_nop 1
	v_add_f32_dpp v17, v17, v17 row_mirror row_mask:0xf bank_mask:0xf bound_ctrl:1
	v_mov_b32_e32 v26, v17
	s_nop 1
	v_permlane16_swap_b32 v17, v26
	s_nop 1
	s_nop 0
	v_add_f32_e32 v17, v17, v26
	v_mov_b32_e32 v26, v17
	s_nop 1
	v_permlane32_swap_b32 v17, v26
	s_nop 1
	s_nop 0
	v_add_f32_e32 v26, v17, v26
	v_mul_f32_e32 v17, v21, v21
	v_fmac_f32_e32 v17, v20, v20
	v_add_f32_e32 v16, v16, v17
	v_fmac_f32_e32 v25, 0xbb800000, v26
	v_fmac_f32_e32 v23, 0xbb800000, v26
	v_add_f32_dpp v16, v16, v16 quad_perm:[1,0,3,2] row_mask:0xf bank_mask:0xf bound_ctrl:1
	v_fmac_f32_e32 v24, 0xbb800000, v26
	v_fmac_f32_e32 v22, 0xbb800000, v26
	v_add_f32_dpp v16, v16, v16 quad_perm:[2,3,0,1] row_mask:0xf bank_mask:0xf bound_ctrl:1
	v_mul_f32_e32 v26, v25, v25
	v_fmac_f32_e32 v26, v24, v24
	v_add_f32_dpp v16, v16, v16 row_half_mirror row_mask:0xf bank_mask:0xf bound_ctrl:1
	s_nop 1
	v_add_f32_dpp v16, v16, v16 row_mirror row_mask:0xf bank_mask:0xf bound_ctrl:1
	v_mov_b32_e32 v17, v16
	s_nop 1
	v_permlane16_swap_b32 v16, v17
	s_nop 1
	s_nop 0
	v_add_f32_e32 v17, v16, v17
	v_mul_f32_e32 v16, v23, v23
	v_fmac_f32_e32 v16, v22, v22
	v_add_f32_e32 v16, v16, v26
	v_mov_b32_e32 v27, v17
	s_nop 1
	v_permlane32_swap_b32 v17, v27
	s_nop 1
	s_nop 0
	v_add_f32_dpp v16, v16, v16 quad_perm:[1,0,3,2] row_mask:0xf bank_mask:0xf bound_ctrl:1
	s_nop 1
	v_add_f32_dpp v16, v16, v16 quad_perm:[2,3,0,1] row_mask:0xf bank_mask:0xf bound_ctrl:1
	s_nop 1
	v_add_f32_dpp v16, v16, v16 row_half_mirror row_mask:0xf bank_mask:0xf bound_ctrl:1
	s_nop 1
	v_add_f32_dpp v16, v16, v16 row_mirror row_mask:0xf bank_mask:0xf bound_ctrl:1
	v_mov_b32_e32 v26, v16
	s_nop 1
	v_permlane16_swap_b32 v16, v26
	s_nop 1
	s_nop 0
	v_add_f32_e32 v16, v16, v26
	v_mov_b32_e32 v26, v16
	s_nop 1
	v_permlane32_swap_b32 v16, v26
	s_nop 1
	s_nop 0
	v_pk_add_f32 v[16:17], v[16:17], v[26:27]
	s_nop 0
	v_pk_fma_f32 v[16:17], v[16:17], s[2:3], v[174:175] op_sel_hi:[1,0,0]
	s_movk_i32 s2, 0x6f
	v_mul_f32_e32 v26, 0x4b800000, v17
	v_cmp_gt_f32_e64 s[34:35], s52, v17
	v_cmp_gt_f32_e32 vcc, s52, v16
	s_nop 0
	v_cndmask_b32_e64 v17, v17, v26, s[34:35]
	v_rsq_f32_e32 v17, v17
	s_nop 0
	v_mul_f32_e32 v26, 0x45800000, v17
	v_cndmask_b32_e64 v26, v17, v26, s[34:35]
	v_mul_f32_e32 v17, 0x4b800000, v16
	v_cndmask_b32_e32 v16, v16, v17, vcc
	v_rsq_f32_e32 v16, v16
	v_pk_mul_f32 v[18:19], v[18:19], v[26:27] op_sel_hi:[1,0]
	v_pk_mul_f32 v[20:21], v[20:21], v[26:27] op_sel_hi:[1,0]
	v_pk_fma_f32 v[18:19], v[2:3], v[18:19], v[6:7]
	v_mul_f32_e32 v17, 0x45800000, v16
	v_cndmask_b32_e32 v16, v16, v17, vcc
	v_pk_fma_f32 v[20:21], v[4:5], v[20:21], v[8:9]
	v_cvt_pk_bf16_f32 v17, v18, v19
	v_cmp_lt_i32_e32 vcc, s2, v15
	v_cvt_pk_bf16_f32 v18, v20, v21
	ds_write2_b32 v14, v17, v18 offset1:1
	v_pk_mul_f32 v[18:19], v[22:23], v[16:17] op_sel_hi:[1,0]
	v_pk_mul_f32 v[16:17], v[24:25], v[16:17] op_sel_hi:[1,0]
	v_pk_fma_f32 v[18:19], v[2:3], v[18:19], v[6:7]
	v_pk_fma_f32 v[16:17], v[4:5], v[16:17], v[8:9]
	s_or_b64 s[92:93], vcc, s[92:93]
	v_cvt_pk_bf16_f32 v16, v16, v17
	v_add_u32_e32 v17, 0x1000, v14
	v_add_u32_e32 v14, 0x2040, v14
	v_cvt_pk_bf16_f32 v18, v18, v19
	ds_write2_b32 v17, v18, v16 offset0:8 offset1:9
	s_andn2_b64 exec, exec, s[92:93]
	s_cbranch_execnz .LBB0_638
.LBB0_639:
	s_waitcnt vmcnt(0)
	s_or_b64 exec, exec, s[76:77]
	v_readlane_b32 s2, v242, 35
	s_waitcnt lgkmcnt(0)
	s_add_u32 s4, s30, s2
	s_addc_u32 s5, s31, 0
	v_lshl_add_u64 v[2:3], s[4:5], 0, v[10:11]
	v_lshl_add_u64 v[2:3], v[2:3], 0, v[76:77]
	s_mov_b64 s[4:5], 0x5700000
	v_mov_b32_e32 v5, 0
	v_lshl_add_u64 v[28:29], v[2:3], 0, s[4:5]
	v_mov_b32_e32 v4, v5
	v_mov_b32_e32 v3, v5
	v_mov_b32_e32 v2, v5
	v_mov_b32_e32 v9, v5
	v_mov_b32_e32 v8, v5
	v_mov_b32_e32 v7, v5
	v_mov_b32_e32 v6, v5
	v_mov_b32_e32 v15, v5
	v_mov_b32_e32 v14, v5
	v_mov_b32_e32 v13, v5
	v_mov_b32_e32 v12, v5
	v_mov_b32_e32 v19, v5
	v_mov_b32_e32 v18, v5
	v_mov_b32_e32 v17, v5
	v_mov_b32_e32 v16, v5
	s_barrier
	s_and_saveexec_b64 s[30:31], s[28:29]
	s_cbranch_execz .LBB0_643
	v_mov_b32_e32 v2, 0
	s_mov_b32 s48, 0
	s_mov_b64 s[34:35], 0
	v_mov_b32_e32 v24, v162
	v_mov_b32_e32 v25, v161
	v_mov_b32_e32 v3, v2
	v_mov_b32_e32 v4, v2
	v_mov_b32_e32 v5, v2
	v_mov_b32_e32 v16, v2
	v_mov_b32_e32 v17, v2
	v_mov_b32_e32 v18, v2
	v_mov_b32_e32 v19, v2
	v_mov_b32_e32 v12, v2
	v_mov_b32_e32 v13, v2
	v_mov_b32_e32 v14, v2
	v_mov_b32_e32 v15, v2
	v_mov_b32_e32 v6, v2
	v_mov_b32_e32 v7, v2
	v_mov_b32_e32 v8, v2
	v_mov_b32_e32 v9, v2

.LBB0_2429:
	s_ashr_i32 s10, s4, 6
	v_readlane_b32 s4, v242, 39
	s_cmp_eq_u32 s4, 2
	v_readlane_b32 s4, v242, 13
	s_cselect_b64 s[20:21], -1, 0
	v_readlane_b32 s5, v242, 14
	s_and_b64 s[22:23], s[4:5], s[20:21]
	v_readlane_b32 s11, v243, 2
	s_xor_b64 s[4:5], s[22:23], -1
	s_add_i32 s10, s10, s11
	s_mov_b64 s[24:25], s[0:1]
	s_cmpk_gt_i32 s10, 0x7fff
	s_cbranch_scc1 .LBB0_2448
	v_readlane_b32 s26, v242, 37
	v_readlane_b32 s29, v242, 39
	v_readlane_b32 s27, v242, 38
	s_waitcnt lgkmcnt(0)
	s_add_u32 s11, s12, s26
	s_mul_i32 s48, s29, 0xc00
	s_addc_u32 s28, s13, s27
	s_lshl_b64 s[26:27], s[48:49], 2
	s_add_u32 s26, s11, s26
	s_addc_u32 s27, s28, s27
	v_readlane_b32 s34, v242, 32
	s_add_u32 s30, s6, 0x5800000
	s_mul_i32 s11, s34, 3
	s_addc_u32 s31, s7, 0
	s_add_i32 s11, s29, s11
	s_lshl_b32 s28, s11, 10
	s_mov_b32 s29, s49
	s_lshl_b64 s[28:29], s[28:29], 2
	s_add_u32 s16, s16, s28
	s_addc_u32 s17, s17, s29
	v_cndmask_b32_e64 v3, 0, 1, s[20:21]
	s_add_u32 s14, s14, s28
	v_readfirstlane_b32 s11, v3
	s_addc_u32 s15, s15, s29
	s_add_i32 s11, s34, s11
	s_lshl_b32 s11, s11, 1
	s_and_b64 s[22:23], s[22:23], exec
	s_load_dwordx2 s[24:25], s[24:25], 0xd8
	s_cselect_b32 s34, 0, s11
	s_add_i32 s11, s48, 0xc00
	s_and_b64 s[20:21], s[20:21], exec
	s_cselect_b32 s48, 0, s11
	v_lshlrev_b32_e32 v3, 2, v2
	s_lshl_b64 s[20:21], s[48:49], 2
	v_and_b32_e32 v26, 0xfc, v3
	s_add_u32 s35, s12, s20
	v_lshlrev_b32_e32 v4, 1, v26
	v_mov_b32_e32 v5, v11
	s_addc_u32 s40, s13, s21
	v_lshlrev_b32_e32 v10, 2, v26
	s_waitcnt lgkmcnt(0)
	v_lshl_add_u64 v[4:5], s[24:25], 0, v[4:5]
	s_mov_b64 s[12:13], 0x19900000
	s_ashr_i32 s11, s10, 31
	v_lshl_add_u64 v[30:31], v[4:5], 0, s[12:13]
	v_lshl_add_u64 v[12:13], s[26:27], 0, v[10:11]
	s_mov_b64 s[12:13], 0x2000
	s_lshl_b64 s[20:21], s[10:11], 12
	v_lshl_add_u64 v[38:39], v[12:13], 0, s[12:13]
	s_add_u32 s12, s8, s20
	v_lshl_add_u64 v[40:41], s[8:9], 0, v[10:11]
	s_addc_u32 s13, s9, s21
	s_lshl_b64 s[8:9], s[10:11], 11
	v_lshl_add_u64 v[36:37], s[14:15], 0, v[10:11]
	s_add_u32 s14, s24, s8
	s_addc_u32 s15, s25, s9
	v_readlane_b32 s28, v242, 40
	v_lshl_add_u64 v[34:35], s[16:17], 0, v[10:11]
	s_add_u32 s16, s6, s8
	v_readlane_b32 s29, v242, 41
	s_addc_u32 s17, s7, s9
	v_lshl_add_u64 v[28:29], s[18:19], 0, v[10:11]
	v_cndmask_b32_e64 v24, 0.5, 1.0, s[28:29]
	v_or_b32_e32 v4, 0x100, v26
	v_or_b32_e32 v6, 0x200, v26
	v_or_b32_e32 v8, 0x300, v26
	v_and_b32_e32 v2, 63, v2
	s_add_u32 s18, s18, s20
	v_mov_b32_e32 v32, v24
	v_mov_b32_e32 v33, v24
	v_lshlrev_b32_e32 v10, 4, v2
	v_lshlrev_b32_e32 v42, 3, v2
	v_mov_b32_e32 v43, v11
	s_addc_u32 s19, s19, s21
	v_lshlrev_b32_e32 v27, 2, v4
	v_lshlrev_b32_e32 v74, 2, v6
	v_lshlrev_b32_e32 v75, 2, v8
	v_lshrrev_b32_e32 v250, 6, v1
	s_nop 0
	v_readfirstlane_b32 s32, v250
	s_mul_i32 s32, s32, 0x3000
	s_mov_b32 s38, 0
	v_lshlrev_b32_e32 v250, 2, v26
	v_add_u32_e32 v250, s32, v250
	v_add_u32_e32 v251, s32, v42
	s_branch .LBB0_2432

.LBB0_2432:
	s_add_i32 s6, s76, s10
	s_cmp_lt_i32 s6, 0x8000
	s_cselect_b32 s24, s6, s10
	s_cmpk_gt_i32 s10, 0x3fff
	s_cselect_b64 s[6:7], -1, 0
	v_cndmask_b32_e64 v2, 0, 1, s[6:7]
	s_and_b64 s[6:7], s[6:7], exec
	v_readfirstlane_b32 s7, v2
	s_cselect_b32 s6, 0x9000, 0
	s_or_b32 s7, s34, s7
	s_mul_i32 s48, s7, 0x2400
	s_lshl_b64 s[8:9], s[48:49], 2
	s_add_u32 s20, s35, s8
	s_addc_u32 s21, s40, s9
	s_ashr_i32 s25, s24, 31
	s_cmpk_gt_i32 s24, 0x3fff
	s_cselect_b64 s[26:27], -1, 0
	s_and_b64 s[8:9], s[26:27], exec
	s_cselect_b32 s48, 0x9000, 0
	s_add_u32 s22, s20, 0x1000
	s_addc_u32 s23, s21, 0
	s_lshl_b64 s[8:9], s[24:25], 12
	v_lshl_add_u64 v[4:5], v[28:29], 0, s[8:9]
	s_lshl_b64 s[8:9], s[24:25], 11
	v_lshl_add_u64 v[6:7], s[14:15], 0, v[42:43]
	v_lshl_add_u64 v[56:57], v[30:31], 0, s[8:9]
	s_mov_b32 s8, 0x19900000
	s_mov_b32 s7, s49
	v_add_co_u32_e32 v58, vcc, s8, v6
	v_lshl_add_u64 v[2:3], s[18:19], 0, v[10:11]
	s_nop 0
	v_addc_co_u32_e32 v59, vcc, 0, v7, vcc
	v_lshl_add_u64 v[70:71], v[38:39], 0, s[6:7]
	s_cmpk_gt_i32 s24, 0x3fff
	s_cselect_b32 s41, 1, 0
	s_or_b32 s41, s34, s41
	s_mul_i32 s62, s41, 0x2400
	s_mov_b32 s63, 0
	s_lshl_b64 s[62:63], s[62:63], 2
	s_add_u32 s50, s35, s62
	s_addc_u32 s51, s40, s63
	s_add_u32 s54, s50, 0x1000
	s_addc_u32 s55, s51, 0
	v_lshlrev_b32_e32 v234, 2, v26
	v_lshl_add_u64 v[236:237], v[38:39], 0, s[48:49]
	v_mov_b32_e32 v235, 0
	v_lshl_add_u64 v[252:253], v[58:59], 0, v[42:43]
	v_lshl_add_u64 v[254:255], v[56:57], 0, v[42:43]
	s_cmp_lg_u32 s38, 0
	s_cbranch_scc1 lnd_have
	s_mov_b32 m0, s32
	s_nop 0
	global_load_lds_dwordx4 v[2:3], off nt
	global_load_lds_dwordx4 v[2:3], off offset:1024 nt
	global_load_lds_dwordx4 v[2:3], off offset:2048 nt
	global_load_lds_dwordx4 v[2:3], off offset:3072 nt
	s_add_i32 m0, s32, 0x1000
	s_nop 0
	global_load_lds_dwordx4 v[4:5], off nt
	global_load_lds_dwordx4 v[4:5], off offset:1024 nt
	global_load_lds_dwordx4 v[4:5], off offset:2048 nt
	global_load_lds_dwordx4 v[4:5], off offset:3072 nt
	s_add_i32 m0, s32, 0x2000
	s_nop 0
	global_load_lds_dwordx4 v[252:253], off nt
	global_load_lds_dwordx4 v[252:253], off offset:1024 nt
	s_add_i32 m0, s32, 0x2800
	s_nop 0
	global_load_lds_dwordx4 v[254:255], off nt
	global_load_lds_dwordx4 v[254:255], off offset:1024 nt
lnd_have:
	s_mov_b32 s38, 1
	v_readlane_b32 s77, v242, 11
	s_add_i32 s92, s10, s77
	s_add_i32 s93, s76, s92
	s_cmp_lt_i32 s93, 0x8000
	s_cselect_b32 s93, s93, s92
	s_ashr_i32 s97, s93, 31
	s_mov_b32 s96, s93
	s_lshl_b64 s[98:99], s[96:97], 12
	v_lshl_add_u64 v[244:245], v[2:3], 0, s[66:67]
	v_lshl_add_u64 v[246:247], v[28:29], 0, s[98:99]
	s_lshl_b64 s[98:99], s[96:97], 11
	v_lshl_add_u64 v[248:249], v[252:253], 0, s[68:69]
	v_lshl_add_u64 v[252:253], v[30:31], 0, v[42:43]
	v_lshl_add_u64 v[252:253], v[252:253], 0, s[98:99]
	global_load_dwordx4 v[190:193], v[70:71], off
	global_load_dwordx4 v[194:197], v[70:71], off offset:1024
	global_load_dwordx4 v[198:201], v[70:71], off offset:2048
	global_load_dwordx4 v[214:217], v[70:71], off offset:3072
	global_load_dwordx4 v[218:221], v[236:237], off
	global_load_dwordx4 v[222:225], v[236:237], off offset:1024
	global_load_dwordx4 v[226:229], v[236:237], off offset:2048
	global_load_dwordx4 v[230:233], v[236:237], off offset:3072
	global_load_dwordx4 v[84:87], v[34:35], off
	global_load_dwordx4 v[88:91], v[34:35], off offset:1024
	global_load_dwordx4 v[92:95], v[34:35], off offset:2048
	global_load_dwordx4 v[96:99], v[34:35], off offset:3072
	global_load_dwordx4 v[100:103], v[36:37], off
	global_load_dwordx4 v[104:107], v[36:37], off offset:1024
	global_load_dwordx4 v[108:111], v[36:37], off offset:2048
	global_load_dwordx4 v[112:115], v[36:37], off offset:3072
	global_load_dwordx4 v[116:119], v234, s[22:23]
	global_load_dwordx4 v[120:123], v27, s[22:23]
	global_load_dwordx4 v[124:127], v74, s[22:23]
	global_load_dwordx4 v[128:131], v75, s[22:23]
	global_load_dwordx4 v[132:135], v234, s[20:21]
	global_load_dwordx4 v[136:139], v234, s[20:21] offset:1024
	global_load_dwordx4 v[140:143], v234, s[20:21] offset:2048
	global_load_dwordx4 v[144:147], v234, s[20:21] offset:3072
	global_load_dwordx4 v[148:151], v234, s[54:55]
	global_load_dwordx4 v[152:155], v27, s[54:55]
	global_load_dwordx4 v[156:159], v74, s[54:55]
	global_load_dwordx4 v[160:163], v75, s[54:55]
	global_load_dwordx4 v[164:167], v234, s[50:51]
	global_load_dwordx4 v[168:171], v234, s[50:51] offset:1024
	global_load_dwordx4 v[182:185], v234, s[50:51] offset:2048
	global_load_dwordx4 v[186:189], v234, s[50:51] offset:3072
	v_mov_b32_e32 v25, v24
	s_waitcnt vmcnt(32)
	ds_read_b128 v[44:47], v250 offset:0
	ds_read_b128 v[48:51], v250 offset:4096
	ds_read_b64 v[62:63], v251 offset:8192
	ds_read_b64 v[72:73], v251 offset:10240
	ds_read_b128 v[76:79], v250 offset:1024
	ds_read_b128 v[20:23], v250 offset:5120
	ds_read_b64 v[80:81], v251 offset:8704
	ds_read_b64 v[54:55], v251 offset:10752
	ds_read_b128 v[16:19], v250 offset:2048
	ds_read_b128 v[12:15], v250 offset:6144
	ds_read_b64 v[52:53], v251 offset:9216
	ds_read_b64 v[60:61], v251 offset:11264
	ds_read_b128 v[6:9], v250 offset:3072
	ds_read_b128 v[2:5], v250 offset:7168
	ds_read_b64 v[68:69], v251 offset:9728
	ds_read_b64 v[64:65], v251 offset:11776
	s_waitcnt lgkmcnt(0)
	s_cmpk_gt_i32 s92, 0x7fff
	s_cbranch_scc1 lnd_last
	s_mov_b32 m0, s32
	s_nop 0
	global_load_lds_dwordx4 v[244:245], off nt
	global_load_lds_dwordx4 v[244:245], off offset:1024 nt
	global_load_lds_dwordx4 v[244:245], off offset:2048 nt
	global_load_lds_dwordx4 v[244:245], off offset:3072 nt
	s_add_i32 m0, s32, 0x1000
	s_nop 0
	global_load_lds_dwordx4 v[246:247], off nt
	global_load_lds_dwordx4 v[246:247], off offset:1024 nt
	global_load_lds_dwordx4 v[246:247], off offset:2048 nt
	global_load_lds_dwordx4 v[246:247], off offset:3072 nt
	s_add_i32 m0, s32, 0x2000
	s_nop 0
	global_load_lds_dwordx4 v[248:249], off nt
	global_load_lds_dwordx4 v[248:249], off offset:1024 nt
	s_add_i32 m0, s32, 0x2800
	s_nop 0
	global_load_lds_dwordx4 v[252:253], off nt
	global_load_lds_dwordx4 v[252:253], off offset:1024 nt
	s_waitcnt vmcnt(12)
	s_branch lnd_join
lnd_last:
	s_waitcnt vmcnt(0)
lnd_join:
	v_mov_b64_e32 v[56:57], v[190:191]
	v_mov_b64_e32 v[58:59], v[192:193]
	s_mov_b32 s6, 0x3a800000
	s_nop 0
	v_and_b32_e32 v67, 0xffff0000, v63
	v_lshlrev_b32_e32 v66, 16, v63
	v_and_b32_e32 v63, 0xffff0000, v62
	v_lshlrev_b32_e32 v62, 16, v62
	s_nop 0
	v_pk_add_f32 v[58:59], v[58:59], 1.0 op_sel_hi:[1,0]
	v_pk_add_f32 v[56:57], v[56:57], 1.0 op_sel_hi:[1,0]
	v_pk_mul_f32 v[58:59], v[24:25], v[58:59]
	v_pk_mul_f32 v[56:57], v[32:33], v[56:57]
	s_nop 0
	v_pk_mul_f32 v[62:63], v[56:57], v[62:63]
	v_pk_mul_f32 v[56:57], v[58:59], v[66:67]
	v_lshl_add_u64 v[66:67], v[38:39], 0, s[48:49]
	v_pk_fma_f32 v[56:57], v[46:47], s[72:73], v[56:57] op_sel_hi:[1,0,1]
	v_pk_fma_f32 v[58:59], v[44:45], s[72:73], v[62:63] op_sel_hi:[1,0,1]
	v_mov_b64_e32 v[44:45], v[218:219]
	v_mov_b64_e32 v[46:47], v[220:221]
	v_and_b32_e32 v63, 0xffff0000, v73
	v_lshlrev_b32_e32 v62, 16, v73
	v_and_b32_e32 v73, 0xffff0000, v72
	v_lshlrev_b32_e32 v72, 16, v72
	s_nop 0
	v_pk_add_f32 v[46:47], v[46:47], 1.0 op_sel_hi:[1,0]
	v_pk_add_f32 v[44:45], v[44:45], 1.0 op_sel_hi:[1,0]
	v_pk_mul_f32 v[46:47], v[24:25], v[46:47]
	v_pk_mul_f32 v[44:45], v[32:33], v[44:45]
	s_nop 0
	v_pk_mul_f32 v[72:73], v[44:45], v[72:73]
	v_pk_mul_f32 v[44:45], v[46:47], v[62:63]
	v_pk_fma_f32 v[46:47], v[48:49], s[72:73], v[72:73] op_sel_hi:[1,0,1]
	v_pk_fma_f32 v[44:45], v[50:51], s[72:73], v[44:45] op_sel_hi:[1,0,1]
	v_mov_b64_e32 v[48:49], v[194:195]
	v_mov_b64_e32 v[50:51], v[196:197]
	v_and_b32_e32 v63, 0xffff0000, v81
	v_lshlrev_b32_e32 v62, 16, v81
	v_and_b32_e32 v73, 0xffff0000, v80
	v_lshlrev_b32_e32 v72, 16, v80
	s_nop 0
	v_pk_add_f32 v[50:51], v[50:51], 1.0 op_sel_hi:[1,0]
	v_pk_add_f32 v[48:49], v[48:49], 1.0 op_sel_hi:[1,0]
	v_pk_mul_f32 v[50:51], v[24:25], v[50:51]
	v_pk_mul_f32 v[48:49], v[32:33], v[48:49]
	s_nop 0
	v_pk_mul_f32 v[72:73], v[48:49], v[72:73]
	v_pk_mul_f32 v[48:49], v[50:51], v[62:63]
	v_pk_fma_f32 v[50:51], v[76:77], s[72:73], v[72:73] op_sel_hi:[1,0,1]
	v_pk_fma_f32 v[48:49], v[78:79], s[72:73], v[48:49] op_sel_hi:[1,0,1]
	v_mov_b64_e32 v[76:77], v[222:223]
	v_mov_b64_e32 v[78:79], v[224:225]
	v_and_b32_e32 v63, 0xffff0000, v55
	v_lshlrev_b32_e32 v62, 16, v55
	v_and_b32_e32 v55, 0xffff0000, v54
	v_lshlrev_b32_e32 v54, 16, v54
	s_nop 0
	v_pk_add_f32 v[76:77], v[76:77], 1.0 op_sel_hi:[1,0]
	s_nop 0
	v_pk_mul_f32 v[76:77], v[32:33], v[76:77]
	v_pk_add_f32 v[72:73], v[78:79], 1.0 op_sel_hi:[1,0]
	v_pk_mul_f32 v[54:55], v[76:77], v[54:55]
	v_mov_b64_e32 v[76:77], v[198:199]
	v_mov_b64_e32 v[78:79], v[200:201]
	v_pk_mul_f32 v[72:73], v[24:25], v[72:73]
	s_nop 0
	v_pk_mul_f32 v[62:63], v[72:73], v[62:63]
	s_nop 0
	v_pk_add_f32 v[72:73], v[76:77], 1.0 op_sel_hi:[1,0]
	v_pk_fma_f32 v[22:23], v[22:23], s[72:73], v[62:63] op_sel_hi:[1,0,1]
	v_pk_fma_f32 v[62:63], v[20:21], s[72:73], v[54:55] op_sel_hi:[1,0,1]
	v_pk_add_f32 v[54:55], v[78:79], 1.0 op_sel_hi:[1,0]
	v_and_b32_e32 v21, 0xffff0000, v53
	v_lshlrev_b32_e32 v20, 16, v53
	v_and_b32_e32 v53, 0xffff0000, v52
	v_lshlrev_b32_e32 v52, 16, v52
	v_pk_mul_f32 v[54:55], v[24:25], v[54:55]
	v_pk_mul_f32 v[72:73], v[32:33], v[72:73]
	v_pk_mul_f32 v[20:21], v[54:55], v[20:21]
	v_pk_mul_f32 v[72:73], v[72:73], v[52:53]
	v_pk_fma_f32 v[52:53], v[18:19], s[72:73], v[20:21] op_sel_hi:[1,0,1]
	v_pk_fma_f32 v[54:55], v[16:17], s[72:73], v[72:73] op_sel_hi:[1,0,1]
	v_mov_b64_e32 v[16:17], v[226:227]
	v_mov_b64_e32 v[18:19], v[228:229]
	v_and_b32_e32 v21, 0xffff0000, v61
	v_lshlrev_b32_e32 v20, 16, v61
	v_and_b32_e32 v61, 0xffff0000, v60
	v_lshlrev_b32_e32 v60, 16, v60
	s_nop 0
	v_pk_add_f32 v[18:19], v[18:19], 1.0 op_sel_hi:[1,0]
	v_pk_add_f32 v[16:17], v[16:17], 1.0 op_sel_hi:[1,0]
	v_pk_mul_f32 v[18:19], v[24:25], v[18:19]
	v_pk_mul_f32 v[16:17], v[32:33], v[16:17]
	s_nop 0
	v_pk_mul_f32 v[60:61], v[16:17], v[60:61]
	v_pk_mul_f32 v[16:17], v[18:19], v[20:21]
	v_pk_fma_f32 v[60:61], v[12:13], s[72:73], v[60:61] op_sel_hi:[1,0,1]
	v_pk_fma_f32 v[16:17], v[14:15], s[72:73], v[16:17] op_sel_hi:[1,0,1]
	v_mov_b64_e32 v[12:13], v[214:215]
	v_mov_b64_e32 v[14:15], v[216:217]
	v_and_b32_e32 v19, 0xffff0000, v69
	v_lshlrev_b32_e32 v18, 16, v69
	v_and_b32_e32 v21, 0xffff0000, v68
	v_lshlrev_b32_e32 v20, 16, v68
	v_lshl_add_u64 v[70:71], s[12:13], 0, v[10:11]
	s_nop 0
	v_pk_add_f32 v[14:15], v[14:15], 1.0 op_sel_hi:[1,0]
	v_pk_add_f32 v[12:13], v[12:13], 1.0 op_sel_hi:[1,0]
	v_pk_mul_f32 v[14:15], v[24:25], v[14:15]
	v_pk_mul_f32 v[12:13], v[32:33], v[12:13]
	v_pk_mul_f32 v[14:15], v[14:15], v[18:19]
	v_pk_mul_f32 v[12:13], v[12:13], v[20:21]
	v_pk_fma_f32 v[18:19], v[8:9], s[72:73], v[14:15] op_sel_hi:[1,0,1]
	v_pk_fma_f32 v[20:21], v[6:7], s[72:73], v[12:13] op_sel_hi:[1,0,1]
	v_mov_b64_e32 v[6:7], v[230:231]
	v_mov_b64_e32 v[8:9], v[232:233]
	v_and_b32_e32 v15, 0xffff0000, v64
	v_lshlrev_b32_e32 v14, 16, v64
	v_and_b32_e32 v13, 0xffff0000, v65
	v_lshlrev_b32_e32 v12, 16, v65
	s_nop 0
	v_pk_add_f32 v[6:7], v[6:7], 1.0 op_sel_hi:[1,0]
	v_pk_add_f32 v[8:9], v[8:9], 1.0 op_sel_hi:[1,0]
	v_pk_mul_f32 v[6:7], v[32:33], v[6:7]
	v_pk_mul_f32 v[8:9], v[24:25], v[8:9]
	v_pk_mul_f32 v[6:7], v[6:7], v[14:15]
	v_pk_mul_f32 v[8:9], v[8:9], v[12:13]
	v_pk_fma_f32 v[66:67], v[2:3], s[72:73], v[6:7] op_sel_hi:[1,0,1]
	v_add_f32_e32 v2, v58, v59
	v_add_f32_e32 v3, v56, v57
	v_pk_fma_f32 v[64:65], v[4:5], s[72:73], v[8:9] op_sel_hi:[1,0,1]
	v_add_f32_e32 v2, v2, v3
	v_add_f32_e32 v3, v50, v51
	v_add_f32_e32 v4, v48, v49
	v_add_f32_e32 v2, 0, v2
	v_add_f32_e32 v3, v3, v4
	v_add_f32_e32 v2, v2, v3
	v_add_f32_e32 v3, v54, v55
	v_add_f32_e32 v4, v52, v53
	v_add_f32_e32 v3, v3, v4
	v_add_f32_e32 v2, v2, v3
	v_add_f32_e32 v3, v20, v21
	v_add_f32_e32 v4, v18, v19
	v_add_f32_e32 v3, v3, v4
	v_add_f32_e32 v2, v2, v3
	v_add_f32_e32 v3, v46, v47
	v_add_f32_e32 v4, v44, v45
	v_add_f32_e32 v3, v3, v4
	v_add_f32_e32 v4, v62, v63
	v_add_f32_e32 v5, v22, v23
	v_add_f32_e32 v3, 0, v3
	v_add_f32_e32 v4, v4, v5
	v_add_f32_e32 v3, v3, v4
	v_add_f32_e32 v4, v60, v61
	v_add_f32_e32 v5, v16, v17
	v_add_f32_dpp v2, v2, v2 quad_perm:[1,0,3,2] row_mask:0xf bank_mask:0xf bound_ctrl:1
	v_add_f32_e32 v4, v4, v5
	v_add_f32_e32 v3, v3, v4
	v_add_f32_dpp v2, v2, v2 quad_perm:[2,3,0,1] row_mask:0xf bank_mask:0xf bound_ctrl:1
	v_add_f32_e32 v4, v66, v67
	v_add_f32_e32 v5, v64, v65
	v_add_f32_dpp v2, v2, v2 row_half_mirror row_mask:0xf bank_mask:0xf bound_ctrl:1
	v_add_f32_e32 v4, v4, v5
	v_add_f32_e32 v4, v3, v4
	v_add_f32_dpp v2, v2, v2 row_mirror row_mask:0xf bank_mask:0xf bound_ctrl:1
	v_mov_b32_e32 v3, v2
	s_nop 1
	v_permlane16_swap_b32 v2, v3
	s_nop 1
	v_cndmask_b32_e64 v25, 0, 1, s[4:5]
	v_add_f32_e32 v2, v2, v3
	v_mov_b32_e32 v3, v2
	s_nop 1
	v_permlane32_swap_b32 v2, v3
	s_nop 1
	s_nop 0
	v_add_f32_e32 v2, v2, v3
	v_fmac_f32_e32 v57, 0xba800000, v2
	v_fmac_f32_e32 v59, 0xba800000, v2
	v_fmamk_f32 v56, v2, 0xba800000, v56
	v_fmamk_f32 v58, v2, 0xba800000, v58
	v_mul_f32_e32 v3, v59, v59
	v_mul_f32_e32 v5, v57, v57
	v_fmac_f32_e32 v3, v58, v58
	v_fmac_f32_e32 v5, v56, v56
	v_fmamk_f32 v49, v2, 0xba800000, v49
	v_fmamk_f32 v51, v2, 0xba800000, v51
	v_add_f32_e32 v3, v3, v5
	v_fmac_f32_e32 v48, 0xba800000, v2
	v_fmac_f32_e32 v50, 0xba800000, v2
	v_mul_f32_e32 v5, v51, v51
	v_mul_f32_e32 v6, v49, v49
	v_fmac_f32_e32 v5, v50, v50
	v_fmac_f32_e32 v6, v48, v48
	v_add_f32_e32 v5, v5, v6
	v_fmamk_f32 v53, v2, 0xba800000, v53
	v_fmamk_f32 v55, v2, 0xba800000, v55
	v_add_f32_e32 v3, v3, v5
	v_fmac_f32_e32 v52, 0xba800000, v2
	v_fmac_f32_e32 v54, 0xba800000, v2
	v_mul_f32_e32 v5, v55, v55
	v_mul_f32_e32 v6, v53, v53
	v_fmac_f32_e32 v5, v54, v54
	v_fmac_f32_e32 v6, v52, v52
	v_add_f32_e32 v5, v5, v6
	v_fmamk_f32 v19, v2, 0xba800000, v19
	v_fmamk_f32 v21, v2, 0xba800000, v21
	v_add_f32_e32 v3, v5, v3
	v_fmac_f32_e32 v18, 0xba800000, v2
	v_fmac_f32_e32 v20, 0xba800000, v2
	v_mul_f32_e32 v2, v21, v21
	v_mul_f32_e32 v5, v19, v19
	v_fmac_f32_e32 v2, v20, v20
	v_fmac_f32_e32 v5, v18, v18
	v_add_f32_e32 v2, v2, v5
	v_add_f32_e32 v2, v2, v3
	s_nop 1
	v_add_f32_dpp v2, v2, v2 quad_perm:[1,0,3,2] row_mask:0xf bank_mask:0xf bound_ctrl:1
	s_nop 1
	v_add_f32_dpp v2, v2, v2 quad_perm:[2,3,0,1] row_mask:0xf bank_mask:0xf bound_ctrl:1
	s_nop 1
	v_add_f32_dpp v2, v2, v2 row_half_mirror row_mask:0xf bank_mask:0xf bound_ctrl:1
	s_nop 1
	v_add_f32_dpp v2, v2, v2 row_mirror row_mask:0xf bank_mask:0xf bound_ctrl:1
	v_mov_b32_e32 v3, v2
	s_nop 1
	v_permlane16_swap_b32 v2, v3
	s_nop 1
	s_nop 0
	v_add_f32_e32 v3, v2, v3
	v_add_f32_dpp v2, v4, v4 quad_perm:[1,0,3,2] row_mask:0xf bank_mask:0xf bound_ctrl:1
	v_mov_b32_e32 v5, v3
	s_nop 1
	v_permlane32_swap_b32 v3, v5
	s_nop 1
	s_nop 0
	v_add_f32_dpp v2, v2, v2 quad_perm:[2,3,0,1] row_mask:0xf bank_mask:0xf bound_ctrl:1
	s_nop 1
	v_add_f32_dpp v2, v2, v2 row_half_mirror row_mask:0xf bank_mask:0xf bound_ctrl:1
	s_nop 1
	v_add_f32_dpp v2, v2, v2 row_mirror row_mask:0xf bank_mask:0xf bound_ctrl:1
	v_mov_b32_e32 v4, v2
	s_nop 1
	v_permlane16_swap_b32 v2, v4
	s_nop 1
	s_nop 0
	v_add_f32_e32 v2, v2, v4
	v_mov_b32_e32 v4, v2
	s_nop 1
	v_permlane32_swap_b32 v2, v4
	s_nop 1
	s_nop 0
	v_add_f32_e32 v2, v2, v4
	v_fmamk_f32 v45, v2, 0xba800000, v45
	v_fmamk_f32 v47, v2, 0xba800000, v47
	v_fmac_f32_e32 v44, 0xba800000, v2
	v_fmac_f32_e32 v46, 0xba800000, v2
	v_mul_f32_e32 v4, v47, v47
	v_mul_f32_e32 v6, v45, v45
	v_fmac_f32_e32 v4, v46, v46
	v_fmac_f32_e32 v6, v44, v44
	v_fmamk_f32 v23, v2, 0xba800000, v23
	v_fmamk_f32 v63, v2, 0xba800000, v63
	v_add_f32_e32 v4, v4, v6
	v_fmac_f32_e32 v22, 0xba800000, v2
	v_fmac_f32_e32 v62, 0xba800000, v2
	v_mul_f32_e32 v6, v63, v63
	v_mul_f32_e32 v7, v23, v23
	v_fmac_f32_e32 v6, v62, v62
	v_fmac_f32_e32 v7, v22, v22
	v_add_f32_e32 v6, v6, v7
	v_fmamk_f32 v17, v2, 0xba800000, v17
	v_fmamk_f32 v61, v2, 0xba800000, v61
	v_add_f32_e32 v4, v4, v6
	v_fmac_f32_e32 v16, 0xba800000, v2
	v_fmac_f32_e32 v60, 0xba800000, v2
	v_mul_f32_e32 v6, v61, v61
	v_mul_f32_e32 v7, v17, v17
	v_fmac_f32_e32 v6, v60, v60
	v_fmac_f32_e32 v7, v16, v16
	v_add_f32_e32 v6, v6, v7
	v_fmamk_f32 v65, v2, 0xba800000, v65
	v_fmamk_f32 v67, v2, 0xba800000, v67
	v_add_f32_e32 v4, v6, v4
	v_fmac_f32_e32 v64, 0xba800000, v2
	v_fmac_f32_e32 v66, 0xba800000, v2
	v_mul_f32_e32 v2, v67, v67
	v_mul_f32_e32 v6, v65, v65
	v_fmac_f32_e32 v2, v66, v66
	v_fmac_f32_e32 v6, v64, v64
	v_add_f32_e32 v2, v2, v6
	v_add_f32_e32 v2, v2, v4
	s_nop 1
	v_add_f32_dpp v2, v2, v2 quad_perm:[1,0,3,2] row_mask:0xf bank_mask:0xf bound_ctrl:1
	s_nop 1
	v_add_f32_dpp v2, v2, v2 quad_perm:[2,3,0,1] row_mask:0xf bank_mask:0xf bound_ctrl:1
	s_nop 1
	v_add_f32_dpp v2, v2, v2 row_half_mirror row_mask:0xf bank_mask:0xf bound_ctrl:1
	s_nop 1
	v_add_f32_dpp v2, v2, v2 row_mirror row_mask:0xf bank_mask:0xf bound_ctrl:1
	v_mov_b32_e32 v4, v2
	s_nop 1
	v_permlane16_swap_b32 v2, v4
	s_nop 1
	s_nop 0
	v_add_f32_e32 v2, v2, v4
	v_mov_b32_e32 v4, v2
	s_nop 1
	v_permlane32_swap_b32 v2, v4
	s_nop 1
	s_nop 0
	v_pk_add_f32 v[2:3], v[2:3], v[4:5]
	s_nop 0
	v_pk_fma_f32 v[72:73], v[2:3], s[6:7], v[174:175] op_sel_hi:[1,0,0]
	v_cmp_ne_u32_e64 s[6:7], 1, v25
	v_mul_f32_e32 v2, 0x4b800000, v73
	v_cmp_gt_f32_e32 vcc, s52, v73
	v_cmp_gt_f32_e64 s[8:9], s52, v72
	v_lshlrev_b32_e32 v25, 2, v26
	v_cndmask_b32_e32 v2, v73, v2, vcc
	v_rsq_f32_e32 v2, v2
	s_nop 0
	v_mul_f32_e32 v3, 0x45800000, v2
	v_cndmask_b32_e32 v68, v2, v3, vcc
	s_nop 1
	v_mov_b64_e32 v[2:3], v[84:85]
	v_mov_b64_e32 v[4:5], v[86:87]
	s_nop 1
	v_mov_b64_e32 v[6:7], v[100:101]
	v_mov_b64_e32 v[8:9], v[102:103]
	v_pk_mul_f32 v[12:13], v[58:59], v[68:69] op_sel_hi:[1,0]
	v_pk_mul_f32 v[14:15], v[56:57], v[68:69] op_sel_hi:[1,0]
	s_andn2_b64 vcc, exec, s[4:5]
	v_lshl_add_u64 v[56:57], s[16:17], 0, v[42:43]
	v_pk_fma_f32 v[14:15], v[4:5], v[14:15], v[8:9]
	v_pk_fma_f32 v[12:13], v[2:3], v[12:13], v[6:7]
	global_store_dwordx4 v[70:71], v[12:15], off nt
	s_cbranch_vccnz .LBB0_2434
	s_nop 1
	v_mov_b64_e32 v[76:77], v[116:117]
	v_mov_b64_e32 v[78:79], v[118:119]
	s_nop 1
	v_mov_b64_e32 v[80:81], v[132:133]
	v_mov_b64_e32 v[82:83], v[134:135]
	v_pk_add_f32 v[58:59], v[78:79], 1.0 op_sel_hi:[1,0]
	v_pk_add_f32 v[76:77], v[76:77], 1.0 op_sel_hi:[1,0]
	v_pk_fma_f32 v[14:15], v[14:15], v[58:59], v[82:83]
	v_pk_fma_f32 v[12:13], v[12:13], v[76:77], v[80:81]
	s_nop 0
	v_cvt_pk_bf16_f32 v12, v12, v13
	v_cvt_pk_bf16_f32 v13, v14, v15
	v_add_co_u32_e32 v14, vcc, 0x5800000, v56
	s_nop 1
	v_addc_co_u32_e32 v15, vcc, 0, v57, vcc
	global_store_dwordx2 v[14:15], v[12:13], off

.LBB0_2448:
	s_waitcnt vmcnt(0)
	s_and_b64 vcc, exec, s[4:5]
	s_cbranch_vccnz .LBB0_2449
	s_getpc_b64 s[98:99]
